# attention tile loop: 64 scalar v_sub packed into 32 v_pk_add (bit-identical), and the hoisted mask-predicate cluster of the m=0 half moved behind the need_mask branch so unmasked tiles skip it
# speedup vs baseline: 1.0029x; 1.0029x over previous
; #define LAS __attribute__((address_space(3)))
; __device__ __forceinline__ f32x4 mfma16(bf16x8 a, bf16x8 b, f32x4 c) { return __builtin_amdgcn_mfma_f32_16x16x32_bf16(a, b, c, 0, 0, 0); }
; #define ATM(n) do { if ((n) == PROBE_ATT_A) atm_t0 = __builtin_amdgcn_s_memrealtime(); if ((n) == PROBE_ATT_B) atm_acc += __builtin_amdgcn_s_memrealtime() - atm_t0; } while (0)
; #define ATM(n) do { } while (0)
; __device__ __forceinline__ void attn_item(Frame& F, const Args& A, int b, int h, int j) {
;     ...
;         if (64 * i <= ubase + 31) {
;             f32x4 S[2][4];
; #pragma unroll
;             for (int m = 0; m < 2; ++m)
; #pragma unroll
;                 for (int nt = 0; nt < 4; ++nt) S[m][nt] = (f32x4){0.f, 0.f, 0.f, 0.f};
; #pragma unroll
;             for (int nt = 0; nt < 4; ++nt)
; #pragma unroll
;                 for (int ks = 0; ks < 4; ++ks) { const bf16x8 kf = *(const LAS bf16x8*)(lds + AT_KT + buf * AT_TILE + (16 * nt + fr) * AT_STRIDE + (32 * ks + 8 * fq) * 2);
;                     S[0][nt] = mfma16(kf, qf[0][ks], S[0][nt]); S[1][nt] = mfma16(kf, qf[1][ks], S[1][nt]); }
;             ATM(2);
;             const bool need_mask = (i == 3) || (64 * i + 63 > ubase);
;             bf16x8 pb[2][2];
; #pragma unroll
;             for (int m = 0; m < 2; ++m) {
;                 const int uq = ubase + 16 * m + fr;
;                 float mx = -__builtin_inff();
; #pragma unroll
;                 for (int nt = 0; nt < 4; ++nt) { const f32x4 bkv = *(const LAS f32x4*)(CUM + 64 * i + 16 * nt + 4 * fq), rkv = *(const LAS f32x4*)(RSK + buf * 64 + 16 * nt + 4 * fq);
; #pragma unroll
;                     for (int g = 0; g < 4; ++g) S[m][nt][g] = S[m][nt][g] * rkv[g] + (bq[m] - bkv[g]); }
.LBB0_712:
	s_sub_i32 s4, s64, 63
	s_cmp_gt_i32 s4, s73
	s_cbranch_scc1 .LBB0_722
	s_mul_i32 s68, s6, 0x4800
	v_add_u32_e32 v148, s68, v174
	ds_read_b128 v[120:123], v148
	ds_read_b128 v[128:131], v148 offset:64
	s_cmp_gt_i32 s64, s72
	s_cselect_b64 s[96:97], -1, 0
	s_lshl_b32 s4, s6, 8
	s_movk_i32 s10, 0xdf
	s_movk_i32 s6, 0xe0
	s_cmp_le_i32 s64, s72
	s_waitcnt lgkmcnt(1)
	v_mfma_f32_16x16x32_bf16 v[124:127], v[120:123], v[2:5], 0
	ds_read_b128 v[132:135], v148 offset:4672
	ds_read_b128 v[136:139], v148 offset:9280
	ds_read_b128 v[178:181], v148 offset:13888
	v_mfma_f32_16x16x32_bf16 v[120:123], v[120:123], v[18:21], 0
	s_waitcnt lgkmcnt(3)
	v_mfma_f32_16x16x32_bf16 v[124:127], v[128:131], v[6:9], v[124:127]
	v_mfma_f32_16x16x32_bf16 v[120:123], v[128:131], v[22:25], v[120:123]
	ds_read_b128 v[128:131], v148 offset:128
	s_waitcnt lgkmcnt(0)
	v_mfma_f32_16x16x32_bf16 v[124:127], v[128:131], v[10:13], v[124:127]
	v_mfma_f32_16x16x32_bf16 v[120:123], v[128:131], v[26:29], v[120:123]
	ds_read_b128 v[128:131], v148 offset:192
	s_waitcnt lgkmcnt(0)
	v_mfma_f32_16x16x32_bf16 v[140:143], v[128:131], v[30:33], v[120:123]
	s_nop 4
	ds_read_b128 v[120:123], v148 offset:4608
	v_mfma_f32_16x16x32_bf16 v[124:127], v[128:131], v[14:17], v[124:127]
	s_waitcnt lgkmcnt(0)
	v_mfma_f32_16x16x32_bf16 v[128:131], v[120:123], v[2:5], 0
	v_mfma_f32_16x16x32_bf16 v[120:123], v[120:123], v[18:21], 0
	v_mfma_f32_16x16x32_bf16 v[128:131], v[132:135], v[6:9], v[128:131]
	v_mfma_f32_16x16x32_bf16 v[120:123], v[132:135], v[22:25], v[120:123]
	ds_read_b128 v[132:135], v148 offset:4736
	s_waitcnt lgkmcnt(0)
	v_mfma_f32_16x16x32_bf16 v[128:131], v[132:135], v[10:13], v[128:131]
	v_mfma_f32_16x16x32_bf16 v[120:123], v[132:135], v[26:29], v[120:123]
	ds_read_b128 v[132:135], v148 offset:4800
	s_waitcnt lgkmcnt(0)
	v_mfma_f32_16x16x32_bf16 v[154:157], v[132:135], v[14:17], v[128:131]
	v_mfma_f32_16x16x32_bf16 v[132:135], v[132:135], v[30:33], v[120:123]
	s_nop 3
	ds_read_b128 v[120:123], v148 offset:9216
	s_waitcnt lgkmcnt(0)
	v_mfma_f32_16x16x32_bf16 v[128:131], v[120:123], v[2:5], 0
	v_mfma_f32_16x16x32_bf16 v[120:123], v[120:123], v[18:21], 0
	v_mfma_f32_16x16x32_bf16 v[128:131], v[136:139], v[6:9], v[128:131]
	v_mfma_f32_16x16x32_bf16 v[120:123], v[136:139], v[22:25], v[120:123]
	ds_read_b128 v[136:139], v148 offset:9344
	s_waitcnt lgkmcnt(0)
	v_mfma_f32_16x16x32_bf16 v[128:131], v[136:139], v[10:13], v[128:131]
	v_mfma_f32_16x16x32_bf16 v[120:123], v[136:139], v[26:29], v[120:123]
	ds_read_b128 v[136:139], v148 offset:9408
	s_waitcnt lgkmcnt(0)
	v_mfma_f32_16x16x32_bf16 v[158:161], v[136:139], v[14:17], v[128:131]
	v_mfma_f32_16x16x32_bf16 v[136:139], v[136:139], v[30:33], v[120:123]
	s_nop 3
	ds_read_b128 v[120:123], v148 offset:13824
	s_waitcnt lgkmcnt(0)
	v_mfma_f32_16x16x32_bf16 v[128:131], v[120:123], v[2:5], 0
	v_mfma_f32_16x16x32_bf16 v[120:123], v[120:123], v[18:21], 0
	v_mfma_f32_16x16x32_bf16 v[128:131], v[178:181], v[6:9], v[128:131]
	v_mfma_f32_16x16x32_bf16 v[120:123], v[178:181], v[22:25], v[120:123]
	ds_read_b128 v[178:181], v148 offset:13952
	s_waitcnt lgkmcnt(0)
	v_mfma_f32_16x16x32_bf16 v[128:131], v[178:181], v[10:13], v[128:131]
	v_mfma_f32_16x16x32_bf16 v[120:123], v[178:181], v[26:29], v[120:123]
	ds_read_b128 v[178:181], v148 offset:14016
	v_add_u32_e32 v148, s64, v146
	v_subrev_u32_e32 v200, 62, v148
	s_waitcnt lgkmcnt(0)
	v_mfma_f32_16x16x32_bf16 v[182:185], v[178:181], v[14:17], v[128:131]
	v_subrev_u32_e32 v194, 61, v148
	v_subrev_u32_e32 v195, 60, v148
	v_cmp_gt_i32_e64 s[52:53], s63, v200
	v_mfma_f32_16x16x32_bf16 v[128:131], v[178:181], v[30:33], v[120:123]
	v_add_u32_e32 v180, s4, v173
	s_nop 1
	ds_read_b128 v[120:123], v175
	ds_read_b128 v[186:189], v180
	v_subrev_u32_e32 v179, 63, v148
	v_cmp_gt_i32_e64 s[14:15], s10, v179
	s_movk_i32 s10, 0xde
	s_waitcnt lgkmcnt(1)
	v_pk_add_f32 v[190:191], v[114:115], v[122:123] neg_lo:[0,1] neg_hi:[0,1]
	v_pk_add_f32 v[120:121], v[114:115], v[120:121] neg_lo:[0,1] neg_hi:[0,1]
	s_waitcnt lgkmcnt(0)
	v_pk_fma_f32 v[122:123], v[124:125], v[186:187], v[120:121]
	v_pk_fma_f32 v[120:121], v[126:127], v[188:189], v[190:191]
	ds_read_b128 v[124:127], v175 offset:64
	ds_read_b128 v[186:189], v180 offset:64
	v_cmp_gt_i32_e64 s[22:23], s10, v179
	s_movk_i32 s10, 0xdd
	v_cmp_gt_i32_e64 s[24:25], s10, v179
	s_waitcnt lgkmcnt(1)
	v_pk_add_f32 v[190:191], v[114:115], v[126:127] neg_lo:[0,1] neg_hi:[0,1]
	v_pk_add_f32 v[124:125], v[114:115], v[124:125] neg_lo:[0,1] neg_hi:[0,1]
	s_waitcnt lgkmcnt(0)
	v_pk_fma_f32 v[126:127], v[154:155], v[186:187], v[124:125]
	v_pk_fma_f32 v[124:125], v[156:157], v[188:189], v[190:191]
	ds_read_b128 v[154:157], v175 offset:128
	ds_read_b128 v[186:189], v180 offset:128
	s_movk_i32 s10, 0xd0
	v_cmp_gt_i32_e64 s[20:21], s10, v179
	s_movk_i32 s10, 0xcf
	s_waitcnt lgkmcnt(1)
	v_pk_add_f32 v[190:191], v[114:115], v[156:157] neg_lo:[0,1] neg_hi:[0,1]
	v_pk_add_f32 v[154:155], v[114:115], v[154:155] neg_lo:[0,1] neg_hi:[0,1]
	s_waitcnt lgkmcnt(0)
	v_pk_fma_f32 v[156:157], v[158:159], v[186:187], v[154:155]
	v_pk_fma_f32 v[154:155], v[160:161], v[188:189], v[190:191]
	ds_read_b128 v[158:161], v175 offset:192
	ds_read_b128 v[186:189], v180 offset:192
	v_cmp_gt_i32_e64 s[26:27], s10, v179
	s_movk_i32 s10, 0xce
	v_cmp_gt_i32_e64 s[28:29], s10, v179
	s_movk_i32 s10, 0xcd
	s_waitcnt lgkmcnt(1)
	v_pk_add_f32 v[160:161], v[114:115], v[160:161] neg_lo:[0,1] neg_hi:[0,1]
	v_pk_add_f32 v[158:159], v[114:115], v[158:159] neg_lo:[0,1] neg_hi:[0,1]
	v_cmp_gt_i32_e64 s[30:31], s10, v179
	s_movk_i32 s10, 0xc0
	s_waitcnt lgkmcnt(0)
	v_pk_fma_f32 v[158:159], v[182:183], v[186:187], v[158:159]
	v_pk_fma_f32 v[160:161], v[184:185], v[188:189], v[160:161]
	s_cbranch_scc1 .LBB0_715
; __device__ __forceinline__ void attn_item(Frame& F, const Args& A, int b, int h, int j) {
;     ...
;                 if (need_mask) {
; #pragma unroll
;                     for (int nt = 0; nt < 4; ++nt)
; #pragma unroll
;                         for (int g = 0; g < 4; ++g) { const int uk = 64 * i + 16 * nt + 4 * fq + g; if (uk > uq || uk < 240) S[m][nt][g] = -__builtin_inff(); }
;                     asm volatile("" ::: "memory"); }
	v_subrev_u32_e32 v186, 47, v148
	v_subrev_u32_e32 v187, 46, v148
	v_subrev_u32_e32 v184, 45, v148
	v_subrev_u32_e32 v188, 44, v148
	v_subrev_u32_e32 v183, 31, v148
	v_subrev_u32_e32 v181, 30, v148
	v_subrev_u32_e32 v182, 29, v148
	v_subrev_u32_e32 v185, 28, v148
	v_cmp_gt_i32_e64 s[12:13], s10, v179
	s_movk_i32 s10, 0xbf
	v_cmp_gt_i32_e64 s[4:5], v179, v145
	v_cmp_gt_i32_e64 s[8:9], s63, v179
	v_cmp_ge_i32_e64 s[18:19], v179, v145
	v_cmp_gt_i32_e64 s[6:7], s6, v179
	v_cmp_gt_i32_e64 s[16:17], s10, v179
	v_cmp_gt_i32_e64 s[10:11], s67, v179
	v_cmp_gt_i32_e32 vcc, s65, v179
	v_cmp_gt_i32_e64 s[48:49], v194, v145
	v_cmp_gt_i32_e64 s[54:55], s63, v194
	v_cmp_gt_i32_e64 s[56:57], v195, v145
	v_cmp_gt_i32_e64 s[58:59], s63, v195
	v_cmp_gt_i32_e64 s[42:43], v186, v145
	v_cmp_gt_i32_e64 s[50:51], v187, v145
	v_cmp_gt_i32_e64 s[46:47], v184, v145
	v_cmp_gt_i32_e64 s[44:45], v188, v145
	v_cmp_gt_i32_e64 s[38:39], v183, v145
	v_cmp_gt_i32_e64 s[36:37], v181, v145
	v_cmp_gt_i32_e64 s[34:35], v182, v145
	v_cmp_gt_i32_e64 s[40:41], v185, v145
	v_mov_b32_e32 v178, s60
	s_or_b64 s[4:5], s[4:5], s[8:9]
	v_cndmask_b32_e64 v122, v122, v178, s[4:5]
	s_or_b64 s[4:5], s[18:19], s[52:53]
	v_cndmask_b32_e64 v123, v123, v166, s[4:5]
	s_or_b64 s[4:5], s[48:49], s[54:55]
	v_cndmask_b32_e64 v120, v120, v166, s[4:5]
	s_or_b64 s[4:5], s[56:57], s[58:59]
	v_cndmask_b32_e64 v121, v121, v166, s[4:5]
	s_or_b64 s[4:5], s[6:7], s[42:43]
	v_cndmask_b32_e64 v126, v126, v178, s[4:5]
	s_or_b64 s[4:5], s[14:15], s[50:51]
	v_cndmask_b32_e64 v127, v127, v166, s[4:5]
	s_or_b64 s[4:5], s[22:23], s[46:47]
	v_cndmask_b32_e64 v124, v124, v166, s[4:5]
	s_or_b64 s[4:5], s[24:25], s[44:45]
	v_cndmask_b32_e64 v125, v125, v166, s[4:5]
	s_or_b64 s[4:5], s[20:21], s[38:39]
	v_cndmask_b32_e64 v156, v156, v178, s[4:5]
	s_or_b64 s[4:5], s[26:27], s[36:37]
	v_cndmask_b32_e64 v157, v157, v166, s[4:5]
	s_or_b64 s[4:5], s[28:29], s[34:35]
	v_cndmask_b32_e64 v154, v154, v166, s[4:5]
	s_or_b64 s[4:5], s[30:31], s[40:41]
	v_add_u32_e32 v178, -15, v148
	v_cndmask_b32_e64 v155, v155, v166, s[4:5]
	v_cmp_gt_i32_e64 s[4:5], v178, v145
	v_mov_b32_e32 v178, s60
	s_or_b64 s[4:5], s[12:13], s[4:5]
	v_cndmask_b32_e64 v158, v158, v178, s[4:5]
	v_add_u32_e32 v178, -14, v148
	v_cmp_gt_i32_e64 s[4:5], v178, v145
	s_or_b64 s[4:5], s[16:17], s[4:5]
	v_add_u32_e32 v178, -13, v148
	v_cndmask_b32_e64 v159, v159, v166, s[4:5]
	v_cmp_gt_i32_e64 s[4:5], v178, v145
	s_or_b64 s[4:5], s[10:11], s[4:5]
	v_add_u32_e32 v148, -12, v148
	v_cndmask_b32_e64 v160, v160, v166, s[4:5]
	v_cmp_gt_i32_e64 s[4:5], v148, v145
	s_or_b64 vcc, vcc, s[4:5]
	v_cndmask_b32_e32 v161, v161, v166, vcc

; __device__ __forceinline__ float max_x16(float x) { auto r = __builtin_amdgcn_permlane16_swap(__float_as_uint(x), __float_as_uint(x), false, false); return fmaxf(__uint_as_float(r[0]), __uint_as_float(r[1])); }
; __device__ __forceinline__ float max_x32(float x) { auto r = __builtin_amdgcn_permlane32_swap(__float_as_uint(x), __float_as_uint(x), false, false); return fmaxf(__uint_as_float(r[0]), __uint_as_float(r[1])); }
; __device__ __forceinline__ unsigned pk2(float lo, float hi) { return pg8::cvt_pk_bf16(lo, hi); }
; __device__ __forceinline__ void attn_item(Frame& F, const Args& A, int b, int h, int j) {
;     ...
;                     for (int g = 0; g < 4; ++g) S[m][nt][g] = S[m][nt][g] * rkv[g] + (bq[m] - bkv[g]); }
;                 if (need_mask) {
; #pragma unroll
;                     for (int nt = 0; nt < 4; ++nt)
; #pragma unroll
;                         for (int g = 0; g < 4; ++g) { const int uk = 64 * i + 16 * nt + 4 * fq + g; if (uk > uq || uk < 240) S[m][nt][g] = -__builtin_inff(); }
;                     asm volatile("" ::: "memory"); }
; #pragma unroll
;                 for (int nt = 0; nt < 4; ++nt)
; #pragma unroll
;                     for (int g = 0; g < 4; ++g) mx = fmaxf(mx, S[m][nt][g]);
;                 mx = max_x32(max_x16(mx));
;                 const float mn = fmaxf(mrow[m], mx);
;                 const float alpha = __builtin_amdgcn_exp2f(mrow[m] - mn); mrow[m] = mn;
;                 float ps = 0.f;
; #pragma unroll
;                 for (int nt = 0; nt < 4; ++nt)
; #pragma unroll
;                     for (int g = 0; g < 4; ++g) { const float p = __builtin_amdgcn_exp2f(S[m][nt][g] - mn); ps += p; S[m][nt][g] = p; }
;                 lrow[m] = lrow[m] * alpha + ps;
;                 if (!__all(alpha == 1.0f)) {
; #pragma unroll
;                     for (int dt = 0; dt < 8; ++dt) O[m][dt] *= alpha; }
; #pragma unroll
;                 for (int k2 = 0; k2 < 2; ++k2) { v4u pw; pw.x = pk2(S[m][2 * k2][0], S[m][2 * k2][1]); pw.y = pk2(S[m][2 * k2][2], S[m][2 * k2][3]); pw.z = pk2(S[m][2 * k2 + 1][0], S[m][2 * k2 + 1][1]); pw.w = pk2(S[m][2 * k2 + 1][2], S[m][2 * k2 + 1][3]);
;                     pb[m][k2] = __builtin_bit_cast(bf16x8, pw); }
.LBB0_717:
	v_pk_add_f32 v[210:211], v[120:121], v[178:179] op_sel_hi:[1,0] neg_lo:[0,1] neg_hi:[0,1]
	v_exp_f32_e32 v190, v210
	v_exp_f32_e32 v191, v211
	v_pk_add_f32 v[212:213], v[126:127], v[178:179] op_sel_hi:[1,0] neg_lo:[0,1] neg_hi:[0,1]
	v_exp_f32_e32 v192, v212
	v_exp_f32_e32 v193, v213
	v_pk_add_f32 v[214:215], v[124:125], v[178:179] op_sel_hi:[1,0] neg_lo:[0,1] neg_hi:[0,1]
	v_exp_f32_e32 v196, v214
	v_exp_f32_e32 v197, v215
	v_pk_add_f32 v[216:217], v[156:157], v[178:179] op_sel_hi:[1,0] neg_lo:[0,1] neg_hi:[0,1]
	v_exp_f32_e32 v156, v216
	v_exp_f32_e32 v157, v217
	v_pk_add_f32 v[210:211], v[154:155], v[178:179] op_sel_hi:[1,0] neg_lo:[0,1] neg_hi:[0,1]
	v_exp_f32_e32 v198, v210
	v_exp_f32_e32 v199, v211
	v_pk_add_f32 v[212:213], v[158:159], v[178:179] op_sel_hi:[1,0] neg_lo:[0,1] neg_hi:[0,1]
	v_exp_f32_e32 v158, v212
	v_pk_add_f32 v[214:215], v[122:123], v[178:179] op_sel_hi:[1,0] neg_lo:[0,1] neg_hi:[0,1]
	v_exp_f32_e32 v159, v213
	v_pk_add_f32 v[216:217], v[160:161], v[178:179] op_sel_hi:[1,0] neg_lo:[0,1] neg_hi:[0,1]
	v_exp_f32_e32 v177, v214
	v_exp_f32_e32 v160, v216
	v_exp_f32_e32 v189, v215
	v_exp_f32_e32 v161, v217
	v_cvt_pk_bf16_f32 v124, v177, v189
	v_cvt_pk_bf16_f32 v125, v190, v191
	v_cvt_pk_bf16_f32 v126, v192, v193
	v_cvt_pk_bf16_f32 v127, v196, v197
	v_cvt_pk_bf16_f32 v120, v156, v157
	v_cvt_pk_bf16_f32 v121, v198, v199
	v_cvt_pk_bf16_f32 v122, v158, v159
	v_cvt_pk_bf16_f32 v123, v160, v161
	ds_read_b128 v[202:205], v175
	ds_read_b128 v[206:209], v180
	s_andn2_b64 vcc, exec, s[96:97]
	s_waitcnt lgkmcnt(1)
	v_pk_add_f32 v[154:155], v[118:119], v[202:203] neg_lo:[0,1] neg_hi:[0,1]
	v_pk_add_f32 v[202:203], v[118:119], v[204:205] neg_lo:[0,1] neg_hi:[0,1]
	s_waitcnt lgkmcnt(0)
	v_pk_fma_f32 v[142:143], v[142:143], v[208:209], v[202:203]
	v_pk_fma_f32 v[140:141], v[140:141], v[206:207], v[154:155]
	ds_read_b128 v[202:205], v175 offset:64
	ds_read_b128 v[206:209], v180 offset:64
	s_waitcnt lgkmcnt(1)
	v_pk_add_f32 v[154:155], v[118:119], v[202:203] neg_lo:[0,1] neg_hi:[0,1]
	v_pk_add_f32 v[202:203], v[118:119], v[204:205] neg_lo:[0,1] neg_hi:[0,1]
	s_waitcnt lgkmcnt(0)
	v_pk_fma_f32 v[134:135], v[134:135], v[208:209], v[202:203]
	v_pk_fma_f32 v[154:155], v[132:133], v[206:207], v[154:155]
	ds_read_b128 v[202:205], v175 offset:128
	ds_read_b128 v[206:209], v180 offset:128
	s_waitcnt lgkmcnt(1)
	v_pk_add_f32 v[202:203], v[118:119], v[202:203] neg_lo:[0,1] neg_hi:[0,1]
	v_pk_add_f32 v[132:133], v[118:119], v[204:205] neg_lo:[0,1] neg_hi:[0,1]
	s_waitcnt lgkmcnt(0)
	v_pk_fma_f32 v[132:133], v[138:139], v[208:209], v[132:133]
	v_pk_fma_f32 v[136:137], v[136:137], v[206:207], v[202:203]
	ds_read_b128 v[202:205], v175 offset:192
	ds_read_b128 v[206:209], v180 offset:192
	s_waitcnt lgkmcnt(1)
	v_pk_add_f32 v[138:139], v[118:119], v[202:203] neg_lo:[0,1] neg_hi:[0,1]
	v_pk_add_f32 v[202:203], v[118:119], v[204:205] neg_lo:[0,1] neg_hi:[0,1]
	s_waitcnt lgkmcnt(0)
	v_pk_fma_f32 v[130:131], v[130:131], v[208:209], v[202:203]
	v_pk_fma_f32 v[128:129], v[128:129], v[206:207], v[138:139]
	s_cbranch_vccnz .LBB0_719
	v_cmp_gt_i32_e32 vcc, v179, v170
	v_cmp_gt_i32_e64 s[4:5], s63, v179
	v_mov_b32_e32 v138, s60
	s_or_b64 vcc, vcc, s[4:5]
	v_cndmask_b32_e32 v140, v140, v138, vcc
	v_cmp_ge_i32_e32 vcc, v179, v170
	v_cmp_gt_i32_e64 s[4:5], s63, v200
	s_or_b64 vcc, vcc, s[4:5]
	v_cndmask_b32_e32 v141, v141, v166, vcc
	v_cmp_gt_i32_e32 vcc, v194, v170
	v_cmp_gt_i32_e64 s[4:5], s63, v194
	s_or_b64 vcc, vcc, s[4:5]
	v_cndmask_b32_e32 v142, v142, v166, vcc
	v_cmp_gt_i32_e32 vcc, v195, v170
	v_cmp_gt_i32_e64 s[4:5], s63, v195
	s_or_b64 vcc, vcc, s[4:5]
	s_movk_i32 s4, 0xe0
	v_cndmask_b32_e32 v143, v143, v166, vcc
	v_cmp_gt_i32_e32 vcc, v179, v145
	v_cmp_gt_i32_e64 s[4:5], s4, v179
	s_or_b64 vcc, vcc, s[4:5]
	s_movk_i32 s4, 0xdf
	v_cndmask_b32_e32 v154, v154, v138, vcc
	v_cmp_ge_i32_e32 vcc, v179, v145
	v_cmp_gt_i32_e64 s[4:5], s4, v179
	s_or_b64 vcc, vcc, s[4:5]
	s_movk_i32 s4, 0xde
	v_cndmask_b32_e32 v155, v155, v166, vcc
	v_cmp_gt_i32_e32 vcc, v194, v145
	v_cmp_gt_i32_e64 s[4:5], s4, v179
	s_or_b64 vcc, s[4:5], vcc
	s_movk_i32 s4, 0xdd
	v_cndmask_b32_e32 v134, v134, v166, vcc
	v_cmp_gt_i32_e32 vcc, v195, v145
	v_cmp_gt_i32_e64 s[4:5], s4, v179
	s_or_b64 vcc, s[4:5], vcc
	s_movk_i32 s4, 0xd0
	v_cndmask_b32_e32 v135, v135, v166, vcc
	v_cmp_gt_i32_e32 vcc, v186, v145
	v_cmp_gt_i32_e64 s[4:5], s4, v179
	s_or_b64 vcc, s[4:5], vcc
	s_movk_i32 s4, 0xcf
	v_cndmask_b32_e32 v136, v136, v138, vcc
	v_cmp_gt_i32_e32 vcc, v187, v145
	v_cmp_gt_i32_e64 s[4:5], s4, v179
	s_or_b64 vcc, s[4:5], vcc
	s_movk_i32 s4, 0xce
	v_cndmask_b32_e32 v137, v137, v166, vcc
	v_cmp_gt_i32_e32 vcc, v184, v145
	v_cmp_gt_i32_e64 s[4:5], s4, v179
	s_or_b64 vcc, s[4:5], vcc
	s_movk_i32 s4, 0xcd
	v_cndmask_b32_e32 v132, v132, v166, vcc
	v_cmp_gt_i32_e32 vcc, v188, v145
	v_cmp_gt_i32_e64 s[4:5], s4, v179
	s_or_b64 vcc, s[4:5], vcc
	s_movk_i32 s4, 0xc0
	v_cndmask_b32_e32 v133, v133, v166, vcc
	v_cmp_gt_i32_e32 vcc, v183, v145
	v_cmp_gt_i32_e64 s[4:5], s4, v179
	s_or_b64 vcc, s[4:5], vcc
	s_movk_i32 s4, 0xbf
	v_cndmask_b32_e32 v128, v128, v138, vcc
	v_cmp_gt_i32_e32 vcc, v181, v145
	v_cmp_gt_i32_e64 s[4:5], s4, v179
	s_or_b64 vcc, s[4:5], vcc
	v_cndmask_b32_e32 v129, v129, v166, vcc
	v_cmp_gt_i32_e32 vcc, v182, v145
	v_cmp_gt_i32_e64 s[4:5], s67, v179
	s_or_b64 vcc, s[4:5], vcc
	v_cndmask_b32_e32 v130, v130, v166, vcc
	v_cmp_gt_i32_e32 vcc, v185, v145
	v_cmp_gt_i32_e64 s[4:5], s65, v179
	s_or_b64 vcc, s[4:5], vcc
	v_cndmask_b32_e32 v131, v131, v166, vcc

; #define ATM(n) do { } while (0)
; __device__ __forceinline__ void attn_item(Frame& F, const Args& A, int b, int h, int j) {
;     ...
;                 const float mn = fmaxf(mrow[m], mx);
;                 const float alpha = __builtin_amdgcn_exp2f(mrow[m] - mn); mrow[m] = mn;
;                 float ps = 0.f;
; #pragma unroll
;                 for (int nt = 0; nt < 4; ++nt)
; #pragma unroll
;                     for (int g = 0; g < 4; ++g) { const float p = __builtin_amdgcn_exp2f(S[m][nt][g] - mn); ps += p; S[m][nt][g] = p; }
;                 lrow[m] = lrow[m] * alpha + ps;
;                 if (!__all(alpha == 1.0f)) {
; #pragma unroll
;                     for (int dt = 0; dt < 8; ++dt) O[m][dt] *= alpha; }
; #pragma unroll
;                 for (int k2 = 0; k2 < 2; ++k2) { v4u pw; pw.x = pk2(S[m][2 * k2][0], S[m][2 * k2][1]); pw.y = pk2(S[m][2 * k2][2], S[m][2 * k2][3]); pw.z = pk2(S[m][2 * k2 + 1][0], S[m][2 * k2 + 1][1]); pw.w = pk2(S[m][2 * k2 + 1][2], S[m][2 * k2 + 1][3]);
;                     pb[m][k2] = __builtin_bit_cast(bf16x8, pw); }
;             }
;             ATM(3);
;             const unsigned vb = vbase + (unsigned)(buf * AT_TILE);
;             { v2u vp[16]; asm volatile("ds_read_b64_tr_b16 %0, %16 offset:0 \n\tds_read_b64_tr_b16 %1, %16 offset:4608 \n\tds_read_b64_tr_b16 %2, %16 offset:9216 \n\tds_read_b64_tr_b16 %3, %16 offset:13824 \n\tds_read_b64_tr_b16 %4, %16 offset:32 \n\tds_read_b64_tr_b16 %5, %16 offset:4640 \n\tds_read_b64_tr_b16 %6, %16 offset:9248 \n\tds_read_b64_tr_b16 %7, %16 offset:13856 \n\tds_read_b64_tr_b16 %8, %16 offset:64 \n\tds_read_b64_tr_b16 %9, %16 offset:4672 \n\tds_read_b64_tr_b16 %10, %16 offset:9280 \n\tds_read_b64_tr_b16 %11, %16 offset:13888 \n\tds_read_b64_tr_b16 %12, %16 offset:96 \n\tds_read_b64_tr_b16 %13, %16 offset:4704 \n\tds_read_b64_tr_b16 %14, %16 offset:9312 \n\tds_read_b64_tr_b16 %15, %16 offset:13920 \n\ts_waitcnt lgkmcnt(0)" : "=&v"(vp[0]), "=&v"(vp[1]), "=&v"(vp[2]), "=&v"(vp[3]), "=&v"(vp[4]), "=&v"(vp[5]), "=&v"(vp[6]), "=&v"(vp[7]), "=&v"(vp[8]), "=&v"(vp[9]), "=&v"(vp[10]), "=&v"(vp[11]), "=&v"(vp[12]), "=&v"(vp[13]), "=&v"(vp[14]), "=&v"(vp[15]) : "v"(vb) : "memory");
;               { v4u aw; aw.x = vp[0].x; aw.y = vp[0].y; aw.z = vp[1].x; aw.w = vp[1].y; const bf16x8 vfr = __builtin_bit_cast(bf16x8, aw); O[0][0] = mfma16(vfr, pb[0][0], O[0][0]); O[1][0] = mfma16(vfr, pb[1][0], O[1][0]); }
.LBB0_721:
	v_pk_add_f32 v[210:211], v[140:141], v[138:139] op_sel:[0,1] op_sel_hi:[1,1] neg_lo:[0,1] neg_hi:[0,1]
	v_exp_f32_e32 v140, v210
	v_exp_f32_e32 v141, v211
	v_pk_add_f32 v[212:213], v[142:143], v[138:139] op_sel:[0,1] op_sel_hi:[1,1] neg_lo:[0,1] neg_hi:[0,1]
	v_exp_f32_e32 v142, v212
	v_exp_f32_e32 v143, v213
	v_pk_add_f32 v[214:215], v[154:155], v[138:139] op_sel:[0,1] op_sel_hi:[1,1] neg_lo:[0,1] neg_hi:[0,1]
	v_add_f32_e32 v176, 0, v140
	v_exp_f32_e32 v154, v214
	v_add_f32_e32 v176, v141, v176
	v_exp_f32_e32 v155, v215
	v_pk_add_f32 v[216:217], v[134:135], v[138:139] op_sel:[0,1] op_sel_hi:[1,1] neg_lo:[0,1] neg_hi:[0,1]
	v_add_f32_e32 v176, v142, v176
	v_exp_f32_e32 v134, v216
	v_add_f32_e32 v176, v143, v176
	v_exp_f32_e32 v135, v217
	v_pk_add_f32 v[210:211], v[136:137], v[138:139] op_sel:[0,1] op_sel_hi:[1,1] neg_lo:[0,1] neg_hi:[0,1]
	v_add_f32_e32 v176, v154, v176
	v_exp_f32_e32 v136, v210
	v_add_f32_e32 v176, v155, v176
	v_exp_f32_e32 v137, v211
	v_pk_add_f32 v[212:213], v[132:133], v[138:139] op_sel:[0,1] op_sel_hi:[1,1] neg_lo:[0,1] neg_hi:[0,1]
	v_add_f32_e32 v176, v134, v176
	v_exp_f32_e32 v179, v212
	v_add_f32_e32 v176, v135, v176
	v_add_f32_e32 v176, v136, v176
	v_add_f32_e32 v176, v137, v176
	v_add_f32_e32 v132, v179, v176
	v_exp_f32_e32 v176, v213
	v_pk_add_f32 v[214:215], v[128:129], v[138:139] op_sel:[0,1] op_sel_hi:[1,1] neg_lo:[0,1] neg_hi:[0,1]
	v_exp_f32_e32 v180, v214
	v_exp_f32_e32 v181, v215
	v_pk_add_f32 v[216:217], v[130:131], v[138:139] op_sel:[0,1] op_sel_hi:[1,1] neg_lo:[0,1] neg_hi:[0,1]
	v_exp_f32_e32 v182, v216
	v_add_f32_e32 v132, v176, v132
	v_exp_f32_e32 v183, v217
	v_add_f32_e32 v128, v180, v132
	v_add_f32_e32 v128, v181, v128
	v_add_f32_e32 v128, v182, v128
	v_add_f32_e32 v129, v183, v128
	v_add_f32_e32 v128, 0, v177
	v_add_f32_e32 v128, v189, v128
	v_add_f32_e32 v128, v190, v128
	v_add_f32_e32 v128, v191, v128
	v_add_f32_e32 v128, v192, v128
	v_add_f32_e32 v128, v193, v128
	v_add_f32_e32 v128, v196, v128
	v_add_f32_e32 v128, v197, v128
	v_add_f32_e32 v128, v156, v128
	v_add_f32_e32 v128, v157, v128
	v_add_f32_e32 v128, v198, v128
	v_add_f32_e32 v128, v199, v128
	v_add_f32_e32 v128, v158, v128
	v_add_f32_e32 v128, v159, v128
	v_add_f32_e32 v128, v160, v128
	v_add_f32_e32 v128, v161, v128
	v_fmac_f32_e32 v129, v153, v138
	v_fmac_f32_e32 v128, v152, v148
	v_cvt_pk_bf16_f32 v130, v140, v141
	v_cvt_pk_bf16_f32 v131, v142, v143
	v_cvt_pk_bf16_f32 v132, v154, v155
	v_cvt_pk_bf16_f32 v133, v134, v135
	v_cvt_pk_bf16_f32 v134, v136, v137
	v_cvt_pk_bf16_f32 v135, v179, v176
	v_cvt_pk_bf16_f32 v136, v180, v181
	v_cvt_pk_bf16_f32 v137, v182, v183
	v_add_u32_e32 v138, s68, v172
	ds_read_b64_tr_b16 v[196:197], v138 offset:0
	ds_read_b64_tr_b16 v[198:199], v138 offset:4608
	ds_read_b64_tr_b16 v[192:193], v138 offset:9216
	ds_read_b64_tr_b16 v[194:195], v138 offset:13824
	ds_read_b64_tr_b16 v[188:189], v138 offset:32
	ds_read_b64_tr_b16 v[190:191], v138 offset:4640
	ds_read_b64_tr_b16 v[184:185], v138 offset:9248
	ds_read_b64_tr_b16 v[186:187], v138 offset:13856
	ds_read_b64_tr_b16 v[180:181], v138 offset:64
	ds_read_b64_tr_b16 v[182:183], v138 offset:4672
	ds_read_b64_tr_b16 v[156:157], v138 offset:9280
	ds_read_b64_tr_b16 v[158:159], v138 offset:13888
	ds_read_b64_tr_b16 v[152:153], v138 offset:96
	ds_read_b64_tr_b16 v[154:155], v138 offset:4704
	ds_read_b64_tr_b16 v[140:141], v138 offset:9312
	ds_read_b64_tr_b16 v[142:143], v138 offset:13920
	s_waitcnt lgkmcnt(0)
	s_nop 0
	v_mfma_f32_16x16x32_bf16 v[90:93], v[196:199], v[124:127], v[90:93]
	v_mfma_f32_16x16x32_bf16 v[54:57], v[196:199], v[130:133], v[54:57]
	v_mfma_f32_16x16x32_bf16 v[82:85], v[188:191], v[124:127], v[82:85]
	v_mfma_f32_16x16x32_bf16 v[50:53], v[188:191], v[130:133], v[50:53]
	v_mfma_f32_16x16x32_bf16 v[86:89], v[180:183], v[124:127], v[86:89]
	v_mfma_f32_16x16x32_bf16 v[58:61], v[180:183], v[130:133], v[58:61]
	v_mfma_f32_16x16x32_bf16 v[94:97], v[152:155], v[124:127], v[94:97]
	v_mfma_f32_16x16x32_bf16 v[62:65], v[152:155], v[130:133], v[62:65]
	v_mfma_f32_16x16x32_bf16 v[90:93], v[192:195], v[120:123], v[90:93]
	v_mfma_f32_16x16x32_bf16 v[54:57], v[192:195], v[134:137], v[54:57]
	v_mfma_f32_16x16x32_bf16 v[82:85], v[184:187], v[120:123], v[82:85]
	v_mfma_f32_16x16x32_bf16 v[50:53], v[184:187], v[134:137], v[50:53]
	v_mfma_f32_16x16x32_bf16 v[86:89], v[156:159], v[120:123], v[86:89]
	v_mfma_f32_16x16x32_bf16 v[58:61], v[156:159], v[134:137], v[58:61]
	v_mfma_f32_16x16x32_bf16 v[94:97], v[140:143], v[120:123], v[94:97]
	v_mfma_f32_16x16x32_bf16 v[62:65], v[140:143], v[134:137], v[62:65]
	ds_read_b64_tr_b16 v[196:197], v138 offset:128
	ds_read_b64_tr_b16 v[198:199], v138 offset:4736
	ds_read_b64_tr_b16 v[192:193], v138 offset:9344
	ds_read_b64_tr_b16 v[194:195], v138 offset:13952
	ds_read_b64_tr_b16 v[188:189], v138 offset:160
	ds_read_b64_tr_b16 v[190:191], v138 offset:4768
	ds_read_b64_tr_b16 v[184:185], v138 offset:9376
	ds_read_b64_tr_b16 v[186:187], v138 offset:13984
	ds_read_b64_tr_b16 v[180:181], v138 offset:192
	ds_read_b64_tr_b16 v[182:183], v138 offset:4800
	ds_read_b64_tr_b16 v[156:157], v138 offset:9408
	ds_read_b64_tr_b16 v[158:159], v138 offset:14016
	ds_read_b64_tr_b16 v[152:153], v138 offset:224
	ds_read_b64_tr_b16 v[154:155], v138 offset:4832
	ds_read_b64_tr_b16 v[140:141], v138 offset:9440
	ds_read_b64_tr_b16 v[142:143], v138 offset:14048
	s_waitcnt lgkmcnt(0)
	s_nop 0
	v_mfma_f32_16x16x32_bf16 v[98:101], v[196:199], v[124:127], v[98:101]
	v_mfma_f32_16x16x32_bf16 v[66:69], v[196:199], v[130:133], v[66:69]
	v_mfma_f32_16x16x32_bf16 v[102:105], v[188:191], v[124:127], v[102:105]
	v_mfma_f32_16x16x32_bf16 v[70:73], v[188:191], v[130:133], v[70:73]
	v_mfma_f32_16x16x32_bf16 v[106:109], v[180:183], v[124:127], v[106:109]
	v_mfma_f32_16x16x32_bf16 v[74:77], v[180:183], v[130:133], v[74:77]
	v_mfma_f32_16x16x32_bf16 v[110:113], v[152:155], v[124:127], v[110:113]
	v_mfma_f32_16x16x32_bf16 v[78:81], v[152:155], v[130:133], v[78:81]
	v_mov_b64_e32 v[152:153], v[128:129]
	v_mfma_f32_16x16x32_bf16 v[98:101], v[192:195], v[120:123], v[98:101]
	v_mfma_f32_16x16x32_bf16 v[66:69], v[192:195], v[134:137], v[66:69]
	v_mfma_f32_16x16x32_bf16 v[102:105], v[184:187], v[120:123], v[102:105]
	v_mfma_f32_16x16x32_bf16 v[70:73], v[184:187], v[134:137], v[70:73]
	v_mfma_f32_16x16x32_bf16 v[106:109], v[156:159], v[120:123], v[106:109]
	v_mfma_f32_16x16x32_bf16 v[74:77], v[156:159], v[134:137], v[74:77]
	v_mfma_f32_16x16x32_bf16 v[110:113], v[140:143], v[120:123], v[110:113]
	v_mfma_f32_16x16x32_bf16 v[78:81], v[140:143], v[134:137], v[78:81]
	s_branch .LBB0_723
